# modulation wait: acquire invalidate issued before the poll loop (overlaps the poll round trip)
# speedup vs baseline: 1.0114x; 1.0114x over previous
; __global__ void __launch_bounds__(NTHREADS, 2) fwd_megakernel(Params p) {
;     ...
;     if (IN(0) && IN(1)) {
;         if (threadIdx.x < 64) { unsigned sp = 0; unsigned* mc = (unsigned*)(ws + WS_BAR) + 3712;
;             while ((unsigned)__builtin_amdgcn_readfirstlane(__hip_atomic_load(mc, __ATOMIC_RELAXED, __HIP_MEMORY_SCOPE_AGENT)) < 96u) { __builtin_amdgcn_s_sleep(2); if (++sp > (1u << 22)) break; }
;             __builtin_amdgcn_fence(__ATOMIC_ACQUIRE, "agent");
;             asm volatile("s_waitcnt vmcnt(0)" ::: "memory"); }
;         __syncthreads();
.LBB0_84:
	s_cmp_gt_i32 s97, 1
	s_cselect_b64 s[4:5], -1, 0
	s_and_b64 s[6:7], s[6:7], s[4:5]
	s_andn2_b64 vcc, exec, s[6:7]
	s_cbranch_vccnz .LBB0_96
	v_cmp_gt_u32_e32 vcc, 64, v170
	s_and_saveexec_b64 s[6:7], vcc
	s_cbranch_execz .LBB0_95
	s_add_u32 s8, s34, 0x83a00
	s_addc_u32 s9, s35, 0
	s_mov_b32 s10, 0x400001
	v_mov_b32_e32 v0, 0
	buffer_inv sc1
	s_branch .LBB0_88

; __global__ void __launch_bounds__(NTHREADS, 2) fwd_megakernel(Params p) {
;     ...
;             __builtin_amdgcn_fence(__ATOMIC_ACQUIRE, "agent");
;             asm volatile("s_waitcnt vmcnt(0)" ::: "memory"); }
.LBB0_94:
	s_waitcnt lgkmcnt(0)
	s_waitcnt vmcnt(0)
